# s5_local: input projection Bu moved from f32 VALU FMAs to the f32 matrix cores (v_mfma_f32_32x32x2_f32, exact f32), scan unrolled with register-resident Bu
# speedup vs baseline: 1.2029x; 1.0140x over previous
.LBB0_1008:
	v_bfe_u32 v87, v55, 4, 1
	v_and_b32_e32 v63, 15, v55
	v_lshlrev_b32_e32 v88, 4, v87
	v_or3_b32 v4, v88, s4, v63
	v_lshl_or_b32 v2, v4, 6, v59
	v_lshlrev_b32_e32 v228, 1, v2
	v_lshl_add_u64 v[0:1], v[228:229], 2, v[50:51]
	v_lshlrev_b32_e32 v228, 4, v2
	v_and_b32_e32 v68, 0xffffffe0, v55
	global_load_dwordx2 v[70:71], v[0:1], off
	v_lshlrev_b64 v[0:1], 2, v[228:229]
	v_ashrrev_i32_e32 v69, 31, v68
	v_lshl_add_u64 v[2:3], v[46:47], 0, v[0:1]
	v_lshl_add_u64 v[0:1], v[48:49], 0, v[0:1]
	v_lshl_or_b32 v228, v4, 12, v85
	v_lshlrev_b64 v[72:73], 13, v[68:69]
	global_load_dwordx4 v[32:35], v[2:3], off offset:48
	global_load_dwordx4 v[36:39], v[2:3], off offset:32
	global_load_dwordx4 v[40:43], v[2:3], off offset:16
	global_load_dwordx4 v[90:93], v[2:3], off
	global_load_dwordx4 v[12:15], v[0:1], off offset:48
	global_load_dwordx4 v[16:19], v[0:1], off offset:32
	global_load_dwordx4 v[20:23], v[0:1], off offset:16
	global_load_dwordx4 v[24:27], v[0:1], off
	v_lshl_add_u64 v[0:1], v[52:53], 0, v[228:229]
	v_lshl_add_u64 v[72:73], v[44:45], 0, v[72:73]
	v_lshlrev_b32_e32 v228, 6, v63
	v_lshlrev_b32_e32 v66, 4, v63
	v_lshl_add_u64 v[72:73], v[72:73], 0, v[228:229]
	v_mov_b32_e32 v63, v229
	v_lshl_add_u64 v[72:73], v[72:73], 0, v[62:63]
	v_mov_b32_e32 v65, v229
	global_load_dwordx4 v[28:31], v[0:1], off
	global_load_dwordx4 v[8:11], v[0:1], off offset:64
	global_load_dwordx4 v[4:7], v[0:1], off offset:128
	s_nop 0
	global_load_dwordx4 v[0:3], v[0:1], off offset:192
	v_lshl_add_u64 v[76:77], v[72:73], 0, v[64:65]
	global_load_dwordx4 v[72:75], v[76:77], off offset:16
	s_nop 0
	global_load_dwordx4 v[76:79], v[76:77], off
	s_mov_b32 s5, 0
	v_cmp_eq_u32_e32 vcc, 0, v87
	s_mov_b32 s6, 28
	s_waitcnt vmcnt(0)
	ds_write_b128 v84, v[76:79]
	ds_write_b128 v84, v[72:75] offset:16
	v_and_b32_e32 v208, 31, v59
	v_sub_u32_e32 v209, 31, v208
	v_mov_b32_e32 v217, 0x110
	v_mov_b32_e32 v210, 0xfffffef0
	v_cndmask_b32_e32 v208, v209, v208, vcc
	v_lshrrev_b32_e32 v209, 5, v59
	v_add_u32_e32 v211, 0x20f0, v54
	v_cndmask_b32_e32 v217, v210, v217, vcc
	v_lshlrev_b32_e32 v209, 2, v209
	v_cndmask_b32_e32 v216, v211, v54, vcc
	v_lshl_add_u32 v218, v208, 6, v67
	v_add_u32_e32 v218, v218, v209
	ds_read_b32 v200, v218
	ds_read_b32 v201, v218 offset:8
	ds_read_b32 v202, v218 offset:16
	ds_read_b32 v203, v218 offset:24
	ds_read_b32 v204, v218 offset:32
	ds_read_b32 v205, v218 offset:40
	ds_read_b32 v206, v218 offset:48
	ds_read_b32 v207, v218 offset:56
	v_permlane32_swap_b32_e32 v90, v91
	v_permlane32_swap_b32_e32 v92, v93
	v_permlane32_swap_b32_e32 v40, v41
	v_permlane32_swap_b32_e32 v42, v43
	v_permlane32_swap_b32_e32 v36, v37
	v_permlane32_swap_b32_e32 v38, v39
	v_permlane32_swap_b32_e32 v32, v33
	v_permlane32_swap_b32_e32 v34, v35
	v_permlane32_swap_b32_e32 v24, v25
	v_permlane32_swap_b32_e32 v26, v27
	v_permlane32_swap_b32_e32 v20, v21
	v_permlane32_swap_b32_e32 v22, v23
	v_permlane32_swap_b32_e32 v16, v17
	v_permlane32_swap_b32_e32 v18, v19
	v_permlane32_swap_b32_e32 v12, v13
	v_permlane32_swap_b32_e32 v14, v15
	s_waitcnt lgkmcnt(0)
	s_nop 1
	v_mfma_f32_32x32x2_f32 v[136:151], v200, v90, 0
	v_mfma_f32_32x32x2_f32 v[136:151], v201, v92, v[136:151]
	v_mfma_f32_32x32x2_f32 v[136:151], v202, v40, v[136:151]
	v_mfma_f32_32x32x2_f32 v[136:151], v203, v42, v[136:151]
	v_mfma_f32_32x32x2_f32 v[136:151], v204, v36, v[136:151]
	v_mfma_f32_32x32x2_f32 v[136:151], v205, v38, v[136:151]
	v_mfma_f32_32x32x2_f32 v[136:151], v206, v32, v[136:151]
	v_mfma_f32_32x32x2_f32 v[136:151], v207, v34, v[136:151]
	v_mfma_f32_32x32x2_f32 v[152:167], v200, v91, 0
	v_mfma_f32_32x32x2_f32 v[152:167], v201, v93, v[152:167]
	v_mfma_f32_32x32x2_f32 v[152:167], v202, v41, v[152:167]
	v_mfma_f32_32x32x2_f32 v[152:167], v203, v43, v[152:167]
	v_mfma_f32_32x32x2_f32 v[152:167], v204, v37, v[152:167]
	v_mfma_f32_32x32x2_f32 v[152:167], v205, v39, v[152:167]
	v_mfma_f32_32x32x2_f32 v[152:167], v206, v33, v[152:167]
	v_mfma_f32_32x32x2_f32 v[152:167], v207, v35, v[152:167]
	v_mfma_f32_32x32x2_f32 v[168:183], v200, v24, 0
	v_mfma_f32_32x32x2_f32 v[168:183], v201, v26, v[168:183]
	v_mfma_f32_32x32x2_f32 v[168:183], v202, v20, v[168:183]
	v_mfma_f32_32x32x2_f32 v[168:183], v203, v22, v[168:183]
	v_mfma_f32_32x32x2_f32 v[168:183], v204, v16, v[168:183]
	v_mfma_f32_32x32x2_f32 v[168:183], v205, v18, v[168:183]
	v_mfma_f32_32x32x2_f32 v[168:183], v206, v12, v[168:183]
	v_mfma_f32_32x32x2_f32 v[168:183], v207, v14, v[168:183]
	v_mfma_f32_32x32x2_f32 v[184:199], v200, v25, 0
	v_mfma_f32_32x32x2_f32 v[184:199], v201, v27, v[184:199]
	v_mfma_f32_32x32x2_f32 v[184:199], v202, v21, v[184:199]
	v_mfma_f32_32x32x2_f32 v[184:199], v203, v23, v[184:199]
	v_mfma_f32_32x32x2_f32 v[184:199], v204, v17, v[184:199]
	v_mfma_f32_32x32x2_f32 v[184:199], v205, v19, v[184:199]
	v_mfma_f32_32x32x2_f32 v[184:199], v206, v13, v[184:199]
	v_mfma_f32_32x32x2_f32 v[184:199], v207, v15, v[184:199]
	s_nop 15
	s_nop 3
	v_permlane32_swap_b32_e32 v136, v152
	v_permlane32_swap_b32_e32 v137, v153
	v_permlane32_swap_b32_e32 v138, v154
	v_permlane32_swap_b32_e32 v139, v155
	v_permlane32_swap_b32_e32 v140, v156
	v_permlane32_swap_b32_e32 v141, v157
	v_permlane32_swap_b32_e32 v142, v158
	v_permlane32_swap_b32_e32 v143, v159
	v_permlane32_swap_b32_e32 v144, v160
	v_permlane32_swap_b32_e32 v145, v161
	v_permlane32_swap_b32_e32 v146, v162
	v_permlane32_swap_b32_e32 v147, v163
	v_permlane32_swap_b32_e32 v148, v164
	v_permlane32_swap_b32_e32 v149, v165
	v_permlane32_swap_b32_e32 v150, v166
	v_permlane32_swap_b32_e32 v151, v167
	v_permlane32_swap_b32_e32 v168, v184
	v_permlane32_swap_b32_e32 v169, v185
	v_permlane32_swap_b32_e32 v170, v186
	v_permlane32_swap_b32_e32 v171, v187
	v_permlane32_swap_b32_e32 v172, v188
	v_permlane32_swap_b32_e32 v173, v189
	v_permlane32_swap_b32_e32 v174, v190
	v_permlane32_swap_b32_e32 v175, v191
	v_permlane32_swap_b32_e32 v176, v192
	v_permlane32_swap_b32_e32 v177, v193
	v_permlane32_swap_b32_e32 v178, v194
	v_permlane32_swap_b32_e32 v179, v195
	v_permlane32_swap_b32_e32 v180, v196
	v_permlane32_swap_b32_e32 v181, v197
	v_permlane32_swap_b32_e32 v182, v198
	v_permlane32_swap_b32_e32 v183, v199
	v_mov_b32_e32 v32, 0
	v_mov_b32_e32 v33, 0
	v_mul_f32_e32 v208, v71, v33
	v_mul_f32_e32 v209, v71, v32
	v_fma_f32 v32, v70, v32, -v208
	v_fma_f32 v33, v70, v33, v209
	v_add_f32_e32 v32, v32, v136
	v_add_f32_e32 v33, v33, v168
	v_bfe_u32 v210, v32, 16, 1
	v_bfe_u32 v211, v33, 16, 1
	v_add3_u32 v210, v32, v210, s89
	v_add3_u32 v211, v33, v211, s89
	v_lshrrev_b32_e32 v210, 16, v210
	v_and_or_b32 v210, v211, s75, v210
	ds_write_b32 v216, v210 offset:2048
	v_add_u32_e32 v216, v216, v217
	v_mul_f32_e32 v208, v71, v33
	v_mul_f32_e32 v209, v71, v32
	v_fma_f32 v32, v70, v32, -v208
	v_fma_f32 v33, v70, v33, v209
	v_add_f32_e32 v32, v32, v137
	v_add_f32_e32 v33, v33, v169
	v_bfe_u32 v210, v32, 16, 1
	v_bfe_u32 v211, v33, 16, 1
	v_add3_u32 v210, v32, v210, s89
	v_add3_u32 v211, v33, v211, s89
	v_lshrrev_b32_e32 v210, 16, v210
	v_and_or_b32 v210, v211, s75, v210
	ds_write_b32 v216, v210 offset:2048
	v_add_u32_e32 v216, v216, v217
	v_mul_f32_e32 v208, v71, v33
	v_mul_f32_e32 v209, v71, v32
	v_fma_f32 v32, v70, v32, -v208
	v_fma_f32 v33, v70, v33, v209
	v_add_f32_e32 v32, v32, v138
	v_add_f32_e32 v33, v33, v170
	v_bfe_u32 v210, v32, 16, 1
	v_bfe_u32 v211, v33, 16, 1
	v_add3_u32 v210, v32, v210, s89
	v_add3_u32 v211, v33, v211, s89
	v_lshrrev_b32_e32 v210, 16, v210
	v_and_or_b32 v210, v211, s75, v210
	ds_write_b32 v216, v210 offset:2048
	v_add_u32_e32 v216, v216, v217
	v_mul_f32_e32 v208, v71, v33
	v_mul_f32_e32 v209, v71, v32
	v_fma_f32 v32, v70, v32, -v208
	v_fma_f32 v33, v70, v33, v209
	v_add_f32_e32 v32, v32, v139
	v_add_f32_e32 v33, v33, v171
	v_bfe_u32 v210, v32, 16, 1
	v_bfe_u32 v211, v33, 16, 1
	v_add3_u32 v210, v32, v210, s89
	v_add3_u32 v211, v33, v211, s89
	v_lshrrev_b32_e32 v210, 16, v210
	v_and_or_b32 v210, v211, s75, v210
	ds_write_b32 v216, v210 offset:2048
	v_add_u32_e32 v216, v216, v217
	v_mul_f32_e32 v208, v71, v33
	v_mul_f32_e32 v209, v71, v32
	v_fma_f32 v32, v70, v32, -v208
	v_fma_f32 v33, v70, v33, v209
	v_add_f32_e32 v32, v32, v152
	v_add_f32_e32 v33, v33, v184
	v_bfe_u32 v210, v32, 16, 1
	v_bfe_u32 v211, v33, 16, 1
	v_add3_u32 v210, v32, v210, s89
	v_add3_u32 v211, v33, v211, s89
	v_lshrrev_b32_e32 v210, 16, v210
	v_and_or_b32 v210, v211, s75, v210
	ds_write_b32 v216, v210 offset:2048
	v_add_u32_e32 v216, v216, v217
	v_mul_f32_e32 v208, v71, v33
	v_mul_f32_e32 v209, v71, v32
	v_fma_f32 v32, v70, v32, -v208
	v_fma_f32 v33, v70, v33, v209
	v_add_f32_e32 v32, v32, v153
	v_add_f32_e32 v33, v33, v185
	v_bfe_u32 v210, v32, 16, 1
	v_bfe_u32 v211, v33, 16, 1
	v_add3_u32 v210, v32, v210, s89
	v_add3_u32 v211, v33, v211, s89
	v_lshrrev_b32_e32 v210, 16, v210
	v_and_or_b32 v210, v211, s75, v210
	ds_write_b32 v216, v210 offset:2048
	v_add_u32_e32 v216, v216, v217
	v_mul_f32_e32 v208, v71, v33
	v_mul_f32_e32 v209, v71, v32
	v_fma_f32 v32, v70, v32, -v208
	v_fma_f32 v33, v70, v33, v209
	v_add_f32_e32 v32, v32, v154
	v_add_f32_e32 v33, v33, v186
	v_bfe_u32 v210, v32, 16, 1
	v_bfe_u32 v211, v33, 16, 1
	v_add3_u32 v210, v32, v210, s89
	v_add3_u32 v211, v33, v211, s89
	v_lshrrev_b32_e32 v210, 16, v210
	v_and_or_b32 v210, v211, s75, v210
	ds_write_b32 v216, v210 offset:2048
	v_add_u32_e32 v216, v216, v217
	v_mul_f32_e32 v208, v71, v33
	v_mul_f32_e32 v209, v71, v32
	v_fma_f32 v32, v70, v32, -v208
	v_fma_f32 v33, v70, v33, v209
	v_add_f32_e32 v32, v32, v155
	v_add_f32_e32 v33, v33, v187
	v_bfe_u32 v210, v32, 16, 1
	v_bfe_u32 v211, v33, 16, 1
	v_add3_u32 v210, v32, v210, s89
	v_add3_u32 v211, v33, v211, s89
	v_lshrrev_b32_e32 v210, 16, v210
	v_and_or_b32 v210, v211, s75, v210
	ds_write_b32 v216, v210 offset:2048
	v_add_u32_e32 v216, v216, v217
	v_mul_f32_e32 v208, v71, v33
	v_mul_f32_e32 v209, v71, v32
	v_fma_f32 v32, v70, v32, -v208
	v_fma_f32 v33, v70, v33, v209
	v_add_f32_e32 v32, v32, v140
	v_add_f32_e32 v33, v33, v172
	v_bfe_u32 v210, v32, 16, 1
	v_bfe_u32 v211, v33, 16, 1
	v_add3_u32 v210, v32, v210, s89
	v_add3_u32 v211, v33, v211, s89
	v_lshrrev_b32_e32 v210, 16, v210
	v_and_or_b32 v210, v211, s75, v210
	ds_write_b32 v216, v210 offset:2048
	v_add_u32_e32 v216, v216, v217
	v_mul_f32_e32 v208, v71, v33
	v_mul_f32_e32 v209, v71, v32
	v_fma_f32 v32, v70, v32, -v208
	v_fma_f32 v33, v70, v33, v209
	v_add_f32_e32 v32, v32, v141
	v_add_f32_e32 v33, v33, v173
	v_bfe_u32 v210, v32, 16, 1
	v_bfe_u32 v211, v33, 16, 1
	v_add3_u32 v210, v32, v210, s89
	v_add3_u32 v211, v33, v211, s89
	v_lshrrev_b32_e32 v210, 16, v210
	v_and_or_b32 v210, v211, s75, v210
	ds_write_b32 v216, v210 offset:2048
	v_add_u32_e32 v216, v216, v217
	v_mul_f32_e32 v208, v71, v33
	v_mul_f32_e32 v209, v71, v32
	v_fma_f32 v32, v70, v32, -v208
	v_fma_f32 v33, v70, v33, v209
	v_add_f32_e32 v32, v32, v142
	v_add_f32_e32 v33, v33, v174
	v_bfe_u32 v210, v32, 16, 1
	v_bfe_u32 v211, v33, 16, 1
	v_add3_u32 v210, v32, v210, s89
	v_add3_u32 v211, v33, v211, s89
	v_lshrrev_b32_e32 v210, 16, v210
	v_and_or_b32 v210, v211, s75, v210
	ds_write_b32 v216, v210 offset:2048
	v_add_u32_e32 v216, v216, v217
	v_mul_f32_e32 v208, v71, v33
	v_mul_f32_e32 v209, v71, v32
	v_fma_f32 v32, v70, v32, -v208
	v_fma_f32 v33, v70, v33, v209
	v_add_f32_e32 v32, v32, v143
	v_add_f32_e32 v33, v33, v175
	v_bfe_u32 v210, v32, 16, 1
	v_bfe_u32 v211, v33, 16, 1
	v_add3_u32 v210, v32, v210, s89
	v_add3_u32 v211, v33, v211, s89
	v_lshrrev_b32_e32 v210, 16, v210
	v_and_or_b32 v210, v211, s75, v210
	ds_write_b32 v216, v210 offset:2048
	v_add_u32_e32 v216, v216, v217
	v_mul_f32_e32 v208, v71, v33
	v_mul_f32_e32 v209, v71, v32
	v_fma_f32 v32, v70, v32, -v208
	v_fma_f32 v33, v70, v33, v209
	v_add_f32_e32 v32, v32, v156
	v_add_f32_e32 v33, v33, v188
	v_bfe_u32 v210, v32, 16, 1
	v_bfe_u32 v211, v33, 16, 1
	v_add3_u32 v210, v32, v210, s89
	v_add3_u32 v211, v33, v211, s89
	v_lshrrev_b32_e32 v210, 16, v210
	v_and_or_b32 v210, v211, s75, v210
	ds_write_b32 v216, v210 offset:2048
	v_add_u32_e32 v216, v216, v217
	v_mul_f32_e32 v208, v71, v33
	v_mul_f32_e32 v209, v71, v32
	v_fma_f32 v32, v70, v32, -v208
	v_fma_f32 v33, v70, v33, v209
	v_add_f32_e32 v32, v32, v157
	v_add_f32_e32 v33, v33, v189
	v_bfe_u32 v210, v32, 16, 1
	v_bfe_u32 v211, v33, 16, 1
	v_add3_u32 v210, v32, v210, s89
	v_add3_u32 v211, v33, v211, s89
	v_lshrrev_b32_e32 v210, 16, v210
	v_and_or_b32 v210, v211, s75, v210
	ds_write_b32 v216, v210 offset:2048
	v_add_u32_e32 v216, v216, v217
	v_mul_f32_e32 v208, v71, v33
	v_mul_f32_e32 v209, v71, v32
	v_fma_f32 v32, v70, v32, -v208
	v_fma_f32 v33, v70, v33, v209
	v_add_f32_e32 v32, v32, v158
	v_add_f32_e32 v33, v33, v190
	v_bfe_u32 v210, v32, 16, 1
	v_bfe_u32 v211, v33, 16, 1
	v_add3_u32 v210, v32, v210, s89
	v_add3_u32 v211, v33, v211, s89
	v_lshrrev_b32_e32 v210, 16, v210
	v_and_or_b32 v210, v211, s75, v210
	ds_write_b32 v216, v210 offset:2048
	v_add_u32_e32 v216, v216, v217
	v_mul_f32_e32 v208, v71, v33
	v_mul_f32_e32 v209, v71, v32
	v_fma_f32 v32, v70, v32, -v208
	v_fma_f32 v33, v70, v33, v209
	v_add_f32_e32 v32, v32, v159
	v_add_f32_e32 v33, v33, v191
	v_bfe_u32 v210, v32, 16, 1
	v_bfe_u32 v211, v33, 16, 1
	v_add3_u32 v210, v32, v210, s89
	v_add3_u32 v211, v33, v211, s89
	v_lshrrev_b32_e32 v210, 16, v210
	v_and_or_b32 v210, v211, s75, v210
	ds_write_b32 v216, v210 offset:2048
	v_add_u32_e32 v216, v216, v217
	v_mul_f32_e32 v208, v71, v33
	v_mul_f32_e32 v209, v71, v32
	v_fma_f32 v32, v70, v32, -v208
	v_fma_f32 v33, v70, v33, v209
	v_add_f32_e32 v32, v32, v144
	v_add_f32_e32 v33, v33, v176
	v_bfe_u32 v210, v32, 16, 1
	v_bfe_u32 v211, v33, 16, 1
	v_add3_u32 v210, v32, v210, s89
	v_add3_u32 v211, v33, v211, s89
	v_lshrrev_b32_e32 v210, 16, v210
	v_and_or_b32 v210, v211, s75, v210
	ds_write_b32 v216, v210 offset:2048
	v_add_u32_e32 v216, v216, v217
	v_mul_f32_e32 v208, v71, v33
	v_mul_f32_e32 v209, v71, v32
	v_fma_f32 v32, v70, v32, -v208
	v_fma_f32 v33, v70, v33, v209
	v_add_f32_e32 v32, v32, v145
	v_add_f32_e32 v33, v33, v177
	v_bfe_u32 v210, v32, 16, 1
	v_bfe_u32 v211, v33, 16, 1
	v_add3_u32 v210, v32, v210, s89
	v_add3_u32 v211, v33, v211, s89
	v_lshrrev_b32_e32 v210, 16, v210
	v_and_or_b32 v210, v211, s75, v210
	ds_write_b32 v216, v210 offset:2048
	v_add_u32_e32 v216, v216, v217
	v_mul_f32_e32 v208, v71, v33
	v_mul_f32_e32 v209, v71, v32
	v_fma_f32 v32, v70, v32, -v208
	v_fma_f32 v33, v70, v33, v209
	v_add_f32_e32 v32, v32, v146
	v_add_f32_e32 v33, v33, v178
	v_bfe_u32 v210, v32, 16, 1
	v_bfe_u32 v211, v33, 16, 1
	v_add3_u32 v210, v32, v210, s89
	v_add3_u32 v211, v33, v211, s89
	v_lshrrev_b32_e32 v210, 16, v210
	v_and_or_b32 v210, v211, s75, v210
	ds_write_b32 v216, v210 offset:2048
	v_add_u32_e32 v216, v216, v217
	v_mul_f32_e32 v208, v71, v33
	v_mul_f32_e32 v209, v71, v32
	v_fma_f32 v32, v70, v32, -v208
	v_fma_f32 v33, v70, v33, v209
	v_add_f32_e32 v32, v32, v147
	v_add_f32_e32 v33, v33, v179
	v_bfe_u32 v210, v32, 16, 1
	v_bfe_u32 v211, v33, 16, 1
	v_add3_u32 v210, v32, v210, s89
	v_add3_u32 v211, v33, v211, s89
	v_lshrrev_b32_e32 v210, 16, v210
	v_and_or_b32 v210, v211, s75, v210
	ds_write_b32 v216, v210 offset:2048
	v_add_u32_e32 v216, v216, v217
	v_mul_f32_e32 v208, v71, v33
	v_mul_f32_e32 v209, v71, v32
	v_fma_f32 v32, v70, v32, -v208
	v_fma_f32 v33, v70, v33, v209
	v_add_f32_e32 v32, v32, v160
	v_add_f32_e32 v33, v33, v192
	v_bfe_u32 v210, v32, 16, 1
	v_bfe_u32 v211, v33, 16, 1
	v_add3_u32 v210, v32, v210, s89
	v_add3_u32 v211, v33, v211, s89
	v_lshrrev_b32_e32 v210, 16, v210
	v_and_or_b32 v210, v211, s75, v210
	ds_write_b32 v216, v210 offset:2048
	v_add_u32_e32 v216, v216, v217
	v_mul_f32_e32 v208, v71, v33
	v_mul_f32_e32 v209, v71, v32
	v_fma_f32 v32, v70, v32, -v208
	v_fma_f32 v33, v70, v33, v209
	v_add_f32_e32 v32, v32, v161
	v_add_f32_e32 v33, v33, v193
	v_bfe_u32 v210, v32, 16, 1
	v_bfe_u32 v211, v33, 16, 1
	v_add3_u32 v210, v32, v210, s89
	v_add3_u32 v211, v33, v211, s89
	v_lshrrev_b32_e32 v210, 16, v210
	v_and_or_b32 v210, v211, s75, v210
	ds_write_b32 v216, v210 offset:2048
	v_add_u32_e32 v216, v216, v217
	v_mul_f32_e32 v208, v71, v33
	v_mul_f32_e32 v209, v71, v32
	v_fma_f32 v32, v70, v32, -v208
	v_fma_f32 v33, v70, v33, v209
	v_add_f32_e32 v32, v32, v162
	v_add_f32_e32 v33, v33, v194
	v_bfe_u32 v210, v32, 16, 1
	v_bfe_u32 v211, v33, 16, 1
	v_add3_u32 v210, v32, v210, s89
	v_add3_u32 v211, v33, v211, s89
	v_lshrrev_b32_e32 v210, 16, v210
	v_and_or_b32 v210, v211, s75, v210
	ds_write_b32 v216, v210 offset:2048
	v_add_u32_e32 v216, v216, v217
	v_mul_f32_e32 v208, v71, v33
	v_mul_f32_e32 v209, v71, v32
	v_fma_f32 v32, v70, v32, -v208
	v_fma_f32 v33, v70, v33, v209
	v_add_f32_e32 v32, v32, v163
	v_add_f32_e32 v33, v33, v195
	v_bfe_u32 v210, v32, 16, 1
	v_bfe_u32 v211, v33, 16, 1
	v_add3_u32 v210, v32, v210, s89
	v_add3_u32 v211, v33, v211, s89
	v_lshrrev_b32_e32 v210, 16, v210
	v_and_or_b32 v210, v211, s75, v210
	ds_write_b32 v216, v210 offset:2048
	v_add_u32_e32 v216, v216, v217
	v_mul_f32_e32 v208, v71, v33
	v_mul_f32_e32 v209, v71, v32
	v_fma_f32 v32, v70, v32, -v208
	v_fma_f32 v33, v70, v33, v209
	v_add_f32_e32 v32, v32, v148
	v_add_f32_e32 v33, v33, v180
	v_bfe_u32 v210, v32, 16, 1
	v_bfe_u32 v211, v33, 16, 1
	v_add3_u32 v210, v32, v210, s89
	v_add3_u32 v211, v33, v211, s89
	v_lshrrev_b32_e32 v210, 16, v210
	v_and_or_b32 v210, v211, s75, v210
	ds_write_b32 v216, v210 offset:2048
	v_add_u32_e32 v216, v216, v217
	v_mul_f32_e32 v208, v71, v33
	v_mul_f32_e32 v209, v71, v32
	v_fma_f32 v32, v70, v32, -v208
	v_fma_f32 v33, v70, v33, v209
	v_add_f32_e32 v32, v32, v149
	v_add_f32_e32 v33, v33, v181
	v_bfe_u32 v210, v32, 16, 1
	v_bfe_u32 v211, v33, 16, 1
	v_add3_u32 v210, v32, v210, s89
	v_add3_u32 v211, v33, v211, s89
	v_lshrrev_b32_e32 v210, 16, v210
	v_and_or_b32 v210, v211, s75, v210
	ds_write_b32 v216, v210 offset:2048
	v_add_u32_e32 v216, v216, v217
	v_mul_f32_e32 v208, v71, v33
	v_mul_f32_e32 v209, v71, v32
	v_fma_f32 v32, v70, v32, -v208
	v_fma_f32 v33, v70, v33, v209
	v_add_f32_e32 v32, v32, v150
	v_add_f32_e32 v33, v33, v182
	v_bfe_u32 v210, v32, 16, 1
	v_bfe_u32 v211, v33, 16, 1
	v_add3_u32 v210, v32, v210, s89
	v_add3_u32 v211, v33, v211, s89
	v_lshrrev_b32_e32 v210, 16, v210
	v_and_or_b32 v210, v211, s75, v210
	ds_write_b32 v216, v210 offset:2048
	v_add_u32_e32 v216, v216, v217
	v_mul_f32_e32 v208, v71, v33
	v_mul_f32_e32 v209, v71, v32
	v_fma_f32 v32, v70, v32, -v208
	v_fma_f32 v33, v70, v33, v209
	v_add_f32_e32 v32, v32, v151
	v_add_f32_e32 v33, v33, v183
	v_bfe_u32 v210, v32, 16, 1
	v_bfe_u32 v211, v33, 16, 1
	v_add3_u32 v210, v32, v210, s89
	v_add3_u32 v211, v33, v211, s89
	v_lshrrev_b32_e32 v210, 16, v210
	v_and_or_b32 v210, v211, s75, v210
	ds_write_b32 v216, v210 offset:2048
	v_add_u32_e32 v216, v216, v217
	v_mul_f32_e32 v208, v71, v33
	v_mul_f32_e32 v209, v71, v32
	v_fma_f32 v32, v70, v32, -v208
	v_fma_f32 v33, v70, v33, v209
	v_add_f32_e32 v32, v32, v164
	v_add_f32_e32 v33, v33, v196
	v_bfe_u32 v210, v32, 16, 1
	v_bfe_u32 v211, v33, 16, 1
	v_add3_u32 v210, v32, v210, s89
	v_add3_u32 v211, v33, v211, s89
	v_lshrrev_b32_e32 v210, 16, v210
	v_and_or_b32 v210, v211, s75, v210
	ds_write_b32 v216, v210 offset:2048
	v_add_u32_e32 v216, v216, v217
	v_mul_f32_e32 v208, v71, v33
	v_mul_f32_e32 v209, v71, v32
	v_fma_f32 v32, v70, v32, -v208
	v_fma_f32 v33, v70, v33, v209
	v_add_f32_e32 v32, v32, v165
	v_add_f32_e32 v33, v33, v197
	v_bfe_u32 v210, v32, 16, 1
	v_bfe_u32 v211, v33, 16, 1
	v_add3_u32 v210, v32, v210, s89
	v_add3_u32 v211, v33, v211, s89
	v_lshrrev_b32_e32 v210, 16, v210
	v_and_or_b32 v210, v211, s75, v210
	ds_write_b32 v216, v210 offset:2048
	v_add_u32_e32 v216, v216, v217
	v_mul_f32_e32 v208, v71, v33
	v_mul_f32_e32 v209, v71, v32
	v_fma_f32 v32, v70, v32, -v208
	v_fma_f32 v33, v70, v33, v209
	v_add_f32_e32 v32, v32, v166
	v_add_f32_e32 v33, v33, v198
	v_bfe_u32 v210, v32, 16, 1
	v_bfe_u32 v211, v33, 16, 1
	v_add3_u32 v210, v32, v210, s89
	v_add3_u32 v211, v33, v211, s89
	v_lshrrev_b32_e32 v210, 16, v210
	v_and_or_b32 v210, v211, s75, v210
	ds_write_b32 v216, v210 offset:2048
	v_add_u32_e32 v216, v216, v217
	v_mul_f32_e32 v208, v71, v33
	v_mul_f32_e32 v209, v71, v32
	v_fma_f32 v32, v70, v32, -v208
	v_fma_f32 v33, v70, v33, v209
	v_add_f32_e32 v32, v32, v167
	v_add_f32_e32 v33, v33, v199
	v_bfe_u32 v210, v32, 16, 1
	v_bfe_u32 v211, v33, 16, 1
	v_add3_u32 v210, v32, v210, s89
	v_add3_u32 v211, v33, v211, s89
	v_lshrrev_b32_e32 v210, 16, v210
	v_and_or_b32 v210, v211, s75, v210
	ds_write_b32 v216, v210 offset:2048
	s_movk_i32 s5, 0xffef
	v_and_or_b32 v12, v55, s5, v88
	v_ashrrev_i32_e32 v13, 31, v12
	v_lshlrev_b64 v[12:13], 9, v[12:13]
	v_lshl_add_u64 v[12:13], v[56:57], 0, v[12:13]
	global_store_dwordx2 v[12:13], v[32:33], off
	ds_read_b128 v[12:15], v86 offset:2048
	ds_read_b128 v[20:23], v86 offset:2112
	ds_read_b128 v[16:19], v86 offset:6400
	v_lshlrev_b32_e32 v228, 13, v87
	v_add_u32_e32 v55, s77, v55
	v_cmp_lt_i32_e32 vcc, s86, v55
	s_or_b64 s[2:3], vcc, s[2:3]
	s_waitcnt lgkmcnt(2)
	v_mfma_f32_16x16x32_bf16 v[12:15], v[12:15], v[28:31], 0
	s_waitcnt lgkmcnt(1)
	v_mfma_f32_16x16x32_bf16 v[12:15], v[20:23], v[8:11], v[12:15]
	ds_read_b128 v[20:23], v86 offset:6464
	s_waitcnt lgkmcnt(1)
	v_mfma_f32_16x16x32_bf16 v[16:19], v[16:19], v[28:31], 0
	s_waitcnt lgkmcnt(0)
	v_mfma_f32_16x16x32_bf16 v[8:11], v[20:23], v[8:11], v[16:19]
	s_nop 5
	ds_read_b128 v[16:19], v86 offset:2176
	s_waitcnt lgkmcnt(0)
	v_mfma_f32_16x16x32_bf16 v[12:15], v[16:19], v[4:7], v[12:15]
	ds_read_b128 v[16:19], v86 offset:6528
	s_waitcnt lgkmcnt(0)
	v_mfma_f32_16x16x32_bf16 v[4:7], v[16:19], v[4:7], v[8:11]
	s_nop 2
	ds_read_b128 v[8:11], v86 offset:2240
	s_waitcnt lgkmcnt(0)
	v_mfma_f32_16x16x32_bf16 v[8:11], v[8:11], v[0:3], v[12:15]
	s_nop 2
	ds_read_b128 v[12:15], v86 offset:6592
	s_waitcnt lgkmcnt(0)
	v_mfma_f32_16x16x32_bf16 v[0:3], v[12:15], v[0:3], v[4:7]
	s_nop 2
	v_lshl_add_u64 v[4:5], v[228:229], 0, v[68:69]
	v_or_b32_e32 v4, v4, v58
	v_lshlrev_b32_e32 v228, 2, v66
	v_lshl_add_u64 v[6:7], v[60:61], 0, v[228:229]
	v_lshlrev_b64 v[4:5], 10, v[4:5]
	v_lshl_add_u64 v[12:13], v[6:7], 0, v[4:5]
	global_store_dword v[12:13], v8, off
	global_store_dword v[12:13], v9, off offset:1024
	global_store_dword v[12:13], v10, off offset:2048
	global_store_dword v[12:13], v11, off offset:3072
	v_or_b32_e32 v8, 0x4000, v4
	v_mov_b32_e32 v9, v5
	v_lshl_add_u64 v[8:9], v[6:7], 0, v[8:9]
	global_store_dword v[8:9], v0, off
	v_or_b32_e32 v8, 0x4400, v4
	v_mov_b32_e32 v9, v5
	v_lshl_add_u64 v[8:9], v[6:7], 0, v[8:9]
	global_store_dword v[8:9], v1, off
	v_or_b32_e32 v0, 0x4800, v4
	v_mov_b32_e32 v1, v5
	v_lshl_add_u64 v[0:1], v[6:7], 0, v[0:1]
	v_or_b32_e32 v4, 0x4c00, v4
	global_store_dword v[0:1], v2, off
	v_lshl_add_u64 v[0:1], v[6:7], 0, v[4:5]
	global_store_dword v[0:1], v3, off
	s_andn2_b64 exec, exec, s[2:3]
	s_cbranch_execnz .LBB0_1008
